# attention loop: next-unit draw atomic not waited after prefetch issue; picked up at top of next iteration
# baseline (speedup 1.0000x reference)
_Z10fwd_kernel6Params:
	s_mov_b32 s99, 0
	s_load_dword s25, s[0:1], 0xb8
	s_add_u32 s12, s0, 0xb8
	v_writelane_b32 v246, s0, 0
	s_addc_u32 s13, s1, 0
	s_mov_b32 s86, s2
	v_writelane_b32 v246, s1, 1
	s_waitcnt lgkmcnt(0)
	s_and_b32 s1, s25, 7
	s_cmp_lg_u32 s1, 0
	v_readfirstlane_b32 s62, v0
	s_cbranch_scc1 .LBB0_2
	s_ashr_i32 s2, s86, 31
	s_lshr_b32 s2, s2, 29
	s_add_i32 s2, s86, s2
	s_ashr_i32 s3, s2, 3
	s_and_b32 s2, s2, -8
	s_ashr_i32 s1, s25, 3
	s_sub_i32 s2, s86, s2
	s_mul_i32 s1, s1, s2
	s_add_i32 s86, s1, s3

.LBB0_693:
	s_ashr_i32 s1, s33, 6
	s_mul_hi_i32 s3, s1, 0x55555556
	s_lshr_b32 s4, s3, 31
	s_add_i32 s3, s3, s4
	s_mul_i32 s3, s3, 3
	s_sub_i32 s86, s1, s3
	s_lshl_b32 s78, s86, 1
	s_lshl_b32 s1, s33, 8
	s_and_b32 s79, s1, 0xf00
	s_lshr_b32 s1, 0x1000, s78
	s_add_i32 s1, s1, -1
	s_and_b32 s3, s1, s79
	s_cmp_eq_u32 s3, 0
	s_cselect_b64 s[76:77], -1, 0
	s_waitcnt vmcnt(15)
	v_cndmask_b32_e64 v5, v57, 0, s[76:77]
	v_cndmask_b32_e64 v4, v56, 0, s[76:77]
	v_cndmask_b32_e64 v3, v55, 0, s[76:77]
	v_cndmask_b32_e64 v2, v54, 0, s[76:77]
	s_waitcnt vmcnt(14)
	v_cndmask_b32_e64 v9, v53, 0, s[76:77]
	v_cndmask_b32_e64 v8, v52, 0, s[76:77]
	v_cndmask_b32_e64 v7, v51, 0, s[76:77]
	v_cndmask_b32_e64 v6, v50, 0, s[76:77]
	ds_write_b128 v145, v[2:5]
	v_add_u32_e32 v2, v139, v140
	ds_write_b128 v2, v[6:9] offset:55296
	s_waitcnt vmcnt(13)
	v_cndmask_b32_e64 v5, v65, 0, s[76:77]
	v_cndmask_b32_e64 v4, v64, 0, s[76:77]
	v_cndmask_b32_e64 v3, v63, 0, s[76:77]
	v_cndmask_b32_e64 v2, v62, 0, s[76:77]
	s_waitcnt vmcnt(12)
	v_cndmask_b32_e64 v9, v61, 0, s[76:77]
	v_cndmask_b32_e64 v8, v60, 0, s[76:77]
	v_cndmask_b32_e64 v7, v59, 0, s[76:77]
	v_cndmask_b32_e64 v6, v58, 0, s[76:77]
	ds_write_b128 v145, v[2:5] offset:9216
	ds_write_b128 v146, v[6:9] offset:55296
	s_waitcnt vmcnt(11)
	ds_write_b128 v147, v[66:69]
	s_waitcnt vmcnt(10)
	ds_write_b128 v148, v[70:73] offset:55296
	s_waitcnt vmcnt(9)
	ds_write_b128 v147, v[74:77] offset:9216
	s_waitcnt vmcnt(8)
	ds_write_b128 v149, v[78:81] offset:55296
	s_waitcnt vmcnt(7)
	ds_write_b128 v147, v[82:85] offset:18432
	s_waitcnt vmcnt(6)
	ds_write_b128 v150, v[86:89] offset:55296
	s_waitcnt vmcnt(5)
	ds_write_b128 v147, v[90:93] offset:27648
	s_waitcnt vmcnt(4)
	ds_write_b128 v151, v[94:97] offset:55296
	s_and_saveexec_b64 s[4:5], s[80:81]
	s_cmp_eq_u32 s99, 0
	s_cbranch_scc1 .Latdr_no
	v_readfirstlane_b32 s100, v247
	s_mov_b32 s99, 0
	s_nop 1
	v_add3_u32 v137, s100, v248, 32
.Latdr_no:
	v_mov_b32_e32 v2, s2
	ds_write_b32 v2, v137
	s_or_b64 exec, exec, s[4:5]
	v_mov_b32_e32 v2, s2
	s_waitcnt lgkmcnt(0)
	s_barrier
	ds_read_b32 v2, v2
	s_movk_i32 s4, 0xbf
	s_waitcnt lgkmcnt(0)
	v_readfirstlane_b32 s3, v2
	v_cmp_lt_u32_e64 s[72:73], s4, v2
	s_cmpk_lt_u32 s3, 0xc0
	s_cselect_b64 s[74:75], -1, 0
	s_and_b64 vcc, exec, s[72:73]
	s_cbranch_vccnz .LBB0_699
	s_add_i32 s4, s3, s0
	s_ashr_i32 s80, s4, 4
	s_ashr_i32 s4, s4, 6
	s_mul_hi_i32 s5, s4, 0x55555556
	s_lshr_b32 s81, s5, 31
	s_add_i32 s5, s5, s81
	s_mul_i32 s5, s5, 3
	s_sub_i32 s4, s4, s5
	s_lshl_b32 s5, s4, 1
	s_lshl_b32 s4, s3, 8
	s_lshr_b32 s5, 0x1000, s5
	s_and_b32 s4, s4, 0xf00
	s_add_i32 s5, s5, -1
	s_ashr_i32 s81, s80, 31
	s_and_b32 s5, s5, s4
	s_lshl_b64 vcc, s[80:81], 18
	s_cmp_eq_u32 s5, 0
	v_add_u32_e32 v4, s4, v141
	v_mov_b32_e32 v3, vcc_hi
	v_or_b32_e32 v2, vcc_lo, v138
	s_cbranch_scc1 .LBB0_698
	v_ashrrev_i32_e32 v5, 31, v4
	v_lshlrev_b64 v[6:7], 6, v[4:5]
	v_lshl_add_u64 v[6:7], v[6:7], 0, v[2:3]
	v_lshlrev_b64 v[6:7], 1, v[6:7]
	s_mov_b64 s[80:81], 0x2000
	v_lshl_add_u64 v[8:9], s[82:83], 0, v[6:7]
	v_lshl_add_u64 v[10:11], s[84:85], 0, v[6:7]
	v_lshl_add_u64 v[6:7], v[6:7], 0, s[80:81]
	global_load_dwordx4 v[54:57], v[8:9], off
	global_load_dwordx4 v[50:53], v[10:11], off
	v_lshl_add_u64 v[8:9], s[82:83], 0, v[6:7]
	v_lshl_add_u64 v[6:7], s[84:85], 0, v[6:7]
	global_load_dwordx4 v[62:65], v[8:9], off
	global_load_dwordx4 v[58:61], v[6:7], off

.LBB0_700:
	s_mov_b64 s[80:81], exec
	v_mbcnt_lo_u32_b32 v2, s80, 0
	v_mbcnt_hi_u32_b32 v2, s81, v2
	v_cmp_eq_u32_e32 vcc, 0, v2
	s_and_saveexec_b64 s[4:5], vcc
	s_cbranch_execz .LBB0_702
	s_bcnt1_i32_b64 s80, s[80:81]
	v_mov_b32_e32 v247, s80
	v_readlane_b32 s80, v246, 17
	v_readlane_b32 s81, v246, 18
	s_nop 4
	global_atomic_add v247, v131, v247, s[80:81] sc0
.LBB0_702:
	s_or_b64 exec, exec, s[4:5]
	v_mov_b32_e32 v248, v2
	s_mov_b32 s99, 1
	v_readlane_b32 s80, v246, 5
	v_readlane_b32 s81, v246, 6
